# forgetting-attention loop role B: staging stores and next loads issued between its PV and QK MFMA phases, as in the differential loop
# speedup vs baseline: 1.0140x; 1.0065x over previous
; __device__ __forceinline__ s16x4 vtr(ldsp p) { return __builtin_bit_cast(s16x4, __builtin_amdgcn_ds_read_tr16_b64_v4i16((LAS v4i16_t*)p)); }
; #define MASK_BLOCK() do { if (kt == 0 || kt >= diag0) { \
;             _Pragma("unroll") for (int r = 0; r < 16; ++r) { const int kpp = 64 * kt + crow(r, hi); \
;                 if (kpp < 48 || kpp > q_pp) s0[r] = -INFINITY; \
;                 if (kpp + 32 < 48 || kpp + 32 > q_pp) s1[r] = -INFINITY; } } } while (0)
; #define EXPSUM_BLOCK() do { psa = 0.f; psb = 0.f; \
;             _Pragma("unroll") for (int r = 0; r < 16; ++r) { s0[r] = __builtin_amdgcn_exp2f(s0[r]); s1[r] = __builtin_amdgcn_exp2f(s1[r]); psa += s0[r]; asm("" : "+v"(psa)); psb += s1[r]; asm("" : "+v"(psb)); } } while (0)
; template <bool DIFF>
; __device__ __forceinline__ void attn_unit(const AttnP& A, int b, int h, int qi, ldsp lds) {
;     ...
;             QK_BLOCK();
;             s16x4 vlo[8], vhi[8];
; #pragma unroll
;             for (int t = 0; t < 2; ++t)
; #pragma unroll
;                 for (int j = 0; j < 4; ++j) { vlo[t * 4 + j] = vtr(Vb + trb + (16 * j) * VP + t * 64); vhi[t * 4 + j] = vtr(Vb + trb + (16 * j + 8) * VP + t * 64); }
;             __builtin_amdgcn_sched_barrier(0);
;             MASK_BLOCK();
;             bool full = (kt == kt0);
;             float psa, psb;
;             if (!full) {
;                 EXPSUM_BLOCK();
;                 if (__any(psa + psb > 1.0e18f)) { full = true; QK_BLOCK();
.Lfb_s_top:
	s_bitcmp1_b32 s99, 0
	s_cselect_b32 s74, 0x5500, 0
	s_sub_i32 s75, 0x5500, s74
	v_exp_f32_e32 v106, v66
	v_exp_f32_e32 v124, v50
	v_exp_f32_e32 v107, v67
	v_exp_f32_e32 v125, v51
	v_add_f32_e32 v166, 0, v106
	v_add_f32_e32 v167, 0, v124
	v_exp_f32_e32 v108, v68
	v_exp_f32_e32 v126, v52
	v_add_f32_e32 v166, v107, v166
	v_add_f32_e32 v167, v125, v167
	v_exp_f32_e32 v109, v69
	v_exp_f32_e32 v127, v53
	v_add_f32_e32 v166, v108, v166
	v_add_f32_e32 v167, v126, v167
	v_exp_f32_e32 v110, v70
	v_exp_f32_e32 v128, v54
	v_add_f32_e32 v166, v109, v166
	v_add_f32_e32 v167, v127, v167
	v_exp_f32_e32 v111, v71
	v_exp_f32_e32 v129, v55
	v_add_f32_e32 v166, v110, v166
	v_add_f32_e32 v167, v128, v167
	v_exp_f32_e32 v112, v72
	v_exp_f32_e32 v130, v56
	v_add_f32_e32 v166, v111, v166
	v_add_f32_e32 v167, v129, v167
	v_exp_f32_e32 v113, v73
	v_exp_f32_e32 v131, v57
	v_add_f32_e32 v166, v112, v166
	v_add_f32_e32 v167, v130, v167
	v_exp_f32_e32 v116, v74
	v_exp_f32_e32 v132, v58
	v_add_f32_e32 v166, v113, v166
	v_add_f32_e32 v167, v131, v167
	v_exp_f32_e32 v117, v75
	v_exp_f32_e32 v133, v59
	v_add_f32_e32 v166, v116, v166
	v_add_f32_e32 v167, v132, v167
	v_exp_f32_e32 v118, v76
	v_exp_f32_e32 v134, v60
	v_add_f32_e32 v166, v117, v166
	v_add_f32_e32 v167, v133, v167
	v_exp_f32_e32 v119, v77
	v_exp_f32_e32 v135, v61
	v_add_f32_e32 v166, v118, v166
	v_add_f32_e32 v167, v134, v167
	v_exp_f32_e32 v120, v78
	v_exp_f32_e32 v136, v62
	v_add_f32_e32 v166, v119, v166
	v_add_f32_e32 v167, v135, v167
	v_exp_f32_e32 v121, v79
	v_exp_f32_e32 v137, v63
	v_add_f32_e32 v166, v120, v166
	v_add_f32_e32 v167, v136, v167
	v_exp_f32_e32 v122, v80
	v_exp_f32_e32 v138, v64
	v_add_f32_e32 v166, v121, v166
	v_add_f32_e32 v167, v137, v167
	v_exp_f32_e32 v123, v81
	v_exp_f32_e32 v139, v65
	v_add_f32_e32 v166, v122, v166
	v_add_f32_e32 v167, v138, v167
	s_nop 0
	v_add_f32_e32 v166, v123, v166
	v_add_f32_e32 v167, v139, v167
	v_add_f32_e32 v141, v166, v167
	v_cmp_lt_f32_e32 vcc, s85, v141
	s_cbranch_vccnz .Lfb_s_slow
; __device__ __forceinline__ unsigned cvtpk(float lo, float hi) { f32x2 v = {lo, hi}; bf16x2_t b = __builtin_convertvector(v, bf16x2_t); return __builtin_bit_cast(unsigned, b); }
; template <bool DIFF>
; __device__ __forceinline__ void attn_unit(const AttnP& A, int b, int h, int qi, ldsp lds) {
;     ...
;             bf16x8 pw[4];
; #pragma unroll
;             for (int j = 0; j < 4; ++j) {
;                 u32x4 pk;
;                 if (j < 2) { const int rb = 8 * (j & 1); pk.x = cvtpk(s0[rb], s0[rb + 1]); pk.y = cvtpk(s0[rb + 2], s0[rb + 3]); pk.z = cvtpk(s0[rb + 4], s0[rb + 5]); pk.w = cvtpk(s0[rb + 6], s0[rb + 7]); }
;                 else { const int rb = 8 * (j & 1); pk.x = cvtpk(s1[rb], s1[rb + 1]); pk.y = cvtpk(s1[rb + 2], s1[rb + 3]); pk.z = cvtpk(s1[rb + 4], s1[rb + 5]); pk.w = cvtpk(s1[rb + 6], s1[rb + 7]); }
;                 pw[j] = __builtin_bit_cast(bf16x8, pk);
;             }
;             __builtin_amdgcn_sched_barrier(0);
;             __builtin_amdgcn_s_setprio(1);
; #pragma unroll
;             for (int t = 0; t < 2; ++t)
; #pragma unroll
;                 for (int j = 0; j < 4; ++j) {
;                     const bf16x8 vf = (bf16x8){vlo[t * 4 + j][0], vlo[t * 4 + j][1], vlo[t * 4 + j][2], vlo[t * 4 + j][3], vhi[t * 4 + j][0], vhi[t * 4 + j][1], vhi[t * 4 + j][2], vhi[t * 4 + j][3]};
;                     o[t] = __builtin_amdgcn_mfma_f32_32x32x16_bf16(vf, pw[j], o[t], 0, 0, 0);
;                 }
	v_add_u32_e32 v169, s74, v150
	v_add_u32_e32 v0, s74, v164
	v_add_u32_e32 v168, s75, v161
	ds_read_b64_tr_b16 v[58:59], v168 offset:9216
	ds_read_b64_tr_b16 v[60:61], v168 offset:10752
	ds_read_b64_tr_b16 v[62:63], v168 offset:9280
	ds_read_b64_tr_b16 v[64:65], v168 offset:10816
	ds_read_b64_tr_b16 v[74:75], v168 offset:12288
	ds_read_b64_tr_b16 v[76:77], v168 offset:13824
	ds_read_b64_tr_b16 v[78:79], v168 offset:12352
	ds_read_b64_tr_b16 v[80:81], v168 offset:13888
	ds_read_b64_tr_b16 v[244:245], v168 offset:15360
	ds_read_b64_tr_b16 v[246:247], v168 offset:16896
	v_cvt_pk_bf16_f32 v66, v106, v107
	v_cvt_pk_bf16_f32 v67, v108, v109
	v_cvt_pk_bf16_f32 v68, v110, v111
	v_cvt_pk_bf16_f32 v69, v112, v113
	v_cvt_pk_bf16_f32 v70, v116, v117
	v_cvt_pk_bf16_f32 v71, v118, v119
	v_cvt_pk_bf16_f32 v72, v120, v121
	v_cvt_pk_bf16_f32 v73, v122, v123
	v_cvt_pk_bf16_f32 v50, v124, v125
	v_cvt_pk_bf16_f32 v51, v126, v127
	v_cvt_pk_bf16_f32 v52, v128, v129
	v_cvt_pk_bf16_f32 v53, v130, v131
	v_cvt_pk_bf16_f32 v54, v132, v133
	v_cvt_pk_bf16_f32 v55, v134, v135
	v_cvt_pk_bf16_f32 v56, v136, v137
	v_cvt_pk_bf16_f32 v57, v138, v139
	v_add_f32_e32 v154, v141, v154
	ds_read_b64_tr_b16 v[106:107], v168 offset:15424
	ds_read_b64_tr_b16 v[108:109], v168 offset:16960
	ds_read_b64_tr_b16 v[110:111], v168 offset:18432
	ds_read_b64_tr_b16 v[112:113], v168 offset:19968
	ds_read_b64_tr_b16 v[116:117], v168 offset:18496
	ds_read_b64_tr_b16 v[118:119], v168 offset:20032
	v_mov_b32_e32 v248, s97
	ds_read_b32 v248, v248
	ds_read_b128 v[120:123], v169
	ds_read_b128 v[124:127], v169 offset:4608
	ds_read_b128 v[128:131], v169 offset:32
	ds_read_b128 v[132:135], v169 offset:4640
	ds_read_b128 v[136:139], v169 offset:64
	ds_read_b128 v[170:173], v169 offset:4672
	s_setprio 1
	s_waitcnt lgkmcnt(15)
	v_mfma_f32_32x32x16_bf16 v[18:33], v[58:61], v[66:69], v[18:33]
	v_mfma_f32_32x32x16_bf16 v[2:17], v[62:65], v[66:69], v[2:17]
	v_mfma_f32_32x32x16_bf16 v[18:33], v[74:77], v[70:73], v[18:33]
	v_mfma_f32_32x32x16_bf16 v[2:17], v[78:81], v[70:73], v[2:17]
	s_waitcnt lgkmcnt(13)
	v_mfma_f32_32x32x16_bf16 v[18:33], v[244:247], v[50:53], v[18:33]
	ds_read_b128 v[244:247], v169 offset:96
	s_waitcnt lgkmcnt(12)
	v_mfma_f32_32x32x16_bf16 v[2:17], v[106:109], v[50:53], v[2:17]
	ds_read_b128 v[106:109], v169 offset:4704
	s_waitcnt lgkmcnt(11)
	v_mfma_f32_32x32x16_bf16 v[18:33], v[110:113], v[54:57], v[18:33]
	ds_read_b128 v[110:113], v0 offset:128
	s_waitcnt lgkmcnt(10)
	v_mfma_f32_32x32x16_bf16 v[2:17], v[116:119], v[54:57], v[2:17]
	ds_read_b128 v[116:119], v0 offset:4736
	s_waitcnt vmcnt(0)
	v_add_u32_e32 v115, s75, v156
	ds_write_b128 v115, v[98:101]
	s_and_saveexec_b64 s[0:1], s[44:45]
	v_xor_b32_e32 v0, 0x80000000, v155
	v_cvt_pk_bf16_f32 v0, v0, 0
	v_lshlrev_b32_e32 v249, 16, v0
	v_sub_f32_e64 v249, -v155, v249
	v_cvt_pk_bf16_f32 v162, v249, 0
	v_lshlrev_b32_e32 v162, 16, v162
	v_sub_f32_e32 v249, v249, v162
	v_cvt_pk_bf16_f32 v249, v249, 0
	v_and_or_b32 v112, v0, s83, v162
	v_and_or_b32 v113, v249, s83, 1.0
	v_mov_b32_e32 v115, v1
	v_add_u32_e32 v0, s75, v159
	ds_write_b128 v0, v[112:115] offset:128
	s_mov_b64 exec, s[0:1]
	v_add_u32_e32 v115, s74, v158
	ds_write_b128 v115, v[102:105] offset:9216
	global_load_dwordx4 v[102:105], v[250:251], off
	v_lshl_add_u64 v[250:251], v[250:251], 0, s[26:27]
	global_load_dwordx4 v[98:101], v[152:153], off
	v_lshl_add_u64 v[152:153], v[152:153], 0, s[26:27]
	s_and_saveexec_b64 s[0:1], s[44:45]
	global_load_dword v155, v[252:253], off
	s_mov_b64 exec, s[0:1]
	s_mov_b64 s[0:1], 0x800
	v_lshl_add_u64 v[252:253], v[252:253], 0, s[0:1]
	s_waitcnt lgkmcnt(12)
	v_mfma_f32_32x32x16_bf16 v[66:81], v[120:123], v[90:93], v[34:49]
	s_waitcnt lgkmcnt(11)
	v_mfma_f32_32x32x16_bf16 v[50:65], v[124:127], v[90:93], v[34:49]
	v_sub_f32_e32 v249, v160, v248
	v_cvt_pk_bf16_f32 v162, v249, 0
	v_lshlrev_b32_e32 v162, 16, v162
	s_waitcnt lgkmcnt(10)
	v_mfma_f32_32x32x16_bf16 v[66:81], v[128:131], v[82:85], v[66:81]
	s_waitcnt lgkmcnt(9)
	v_mfma_f32_32x32x16_bf16 v[50:65], v[132:135], v[82:85], v[50:65]
	v_sub_f32_e32 v249, v249, v162
	v_cvt_pk_bf16_f32 v163, v249, 0
	v_and_b32_e32 v157, 0xffff, v163
	v_lshlrev_b32_e32 v163, 16, v163
	s_waitcnt lgkmcnt(8)
	v_mfma_f32_32x32x16_bf16 v[66:81], v[136:139], v[86:89], v[66:81]
	s_waitcnt lgkmcnt(7)
	v_mfma_f32_32x32x16_bf16 v[50:65], v[170:173], v[86:89], v[50:65]
	v_sub_f32_e32 v249, v249, v163
	v_cvt_pk_bf16_f32 v249, v249, 0
	v_or_b32_e32 v162, 0x3f80, v162
	v_lshl_or_b32 v249, v249, 16, v157
	v_cndmask_b32_e64 v140, 0, v114, s[46:47]
	v_cndmask_b32_e64 v142, 0, v249, s[46:47]
	v_cndmask_b32_e64 v141, 0, v162, s[46:47]
	v_mov_b32_e32 v143, v1
	s_waitcnt lgkmcnt(6)
	v_mfma_f32_32x32x16_bf16 v[66:81], v[244:247], v[94:97], v[66:81]
	s_waitcnt lgkmcnt(5)
	v_mfma_f32_32x32x16_bf16 v[50:65], v[106:109], v[94:97], v[50:65]
	s_waitcnt lgkmcnt(4)
	v_mfma_f32_32x32x16_bf16 v[66:81], v[110:113], v[140:143], v[66:81]
	s_waitcnt lgkmcnt(3)
	v_mfma_f32_32x32x16_bf16 v[50:65], v[116:119], v[140:143], v[50:65]
	s_setprio 0
	s_waitcnt lgkmcnt(0)
	s_barrier
	s_add_i32 s99, s99, 1
	s_add_i32 s94, s94, 1
	s_add_i32 s97, s97, 4
	s_add_i32 s98, s98, 64
	s_add_i32 s0, s95, 0
	s_cmp_le_i32 s99, s0
	s_cbranch_scc1 .Lfb_s_top
